# attention queue: static s_setprio 1 for waves in odd HW wave slots (one of the two co-resident blocks), reset after the queue
# baseline (speedup 1.0000x reference)
; DI int TIDX() { int t = threadIdx.x; asm volatile("" : "+v"(t)); return t; }
; DI void phase_mixer(const P& p, int l, const XcdBarrier& xb, char* smem) {
;     ...
;   for (;;) {
;     __syncthreads();
;     if (TIDX() == 0) *sit = atomicAdd(ctr, 1);
;     __syncthreads();
;     const int it = *sit;
;     if (it >= nit) break;
;     attn_dispatch(p, xcd, it, smem);
;   }
.LBB0_2723:
	s_getreg_b32 s40, hwreg(HW_REG_HW_ID, 0, 4)
	s_bitcmp1_b32 s40, 0
	s_cbranch_scc0 .Lattn_prio_done
	s_setprio 1

; DI void phase_mixer(const P& p, int l, const XcdBarrier& xb, char* smem) {
;     ...
;     const int it = *sit;
;     if (it >= nit) break;
;     attn_dispatch(p, xcd, it, smem);
;   }
; }
.LBB0_2779:
	s_setprio 0
	s_mov_b64 s[66:67], 0x1000
	v_readlane_b32 s31, v254, 50
